# v41 with the 48 per-segment s_setprio flips of the three GEMM K-loops deleted (A/B of the flips)
# baseline (speedup 1.0000x reference)
; #define PG8_STAGE(bufoff, gbase, voff) do { _Pragma("unroll") for (int _i = 0; _i < 2; ++_i) \
;         __builtin_amdgcn_global_load_lds((const unsigned*)((const char*)(gbase) + (voff)[_i]), (PG8_LAS unsigned*)(lds + (bufoff) + ldsw + _i * 8192), 16, 0, 0); } while (0)
; #define PG8_LDA(dst, b, h) do { _Pragma("unroll") for (int m = 0; m < 4; ++m) _Pragma("unroll") for (int k = 0; k < 2; ++k) dst[m][k] = *(const PG8_LAS bf16x8*)(lds + PG8_SA(b, h) + aoff + m * 2048 + k * 1024); } while (0)
; #define PG8_LDB(dst, b, h) do { _Pragma("unroll") for (int n = 0; n < 2; ++n) _Pragma("unroll") for (int k = 0; k < 2; ++k) dst[n][k] = *(const PG8_LAS bf16x8*)(lds + PG8_SB(b, h) + boff + n * 2048 + k * 1024); } while (0)
; #define PG8_MMA(ai, bj, At, Bt) do { __builtin_amdgcn_s_setprio(1); _Pragma("unroll") for (int m = 0; m < 4; ++m) _Pragma("unroll") for (int n = 0; n < 2; ++n) _Pragma("unroll") for (int k = 0; k < 2; ++k) \
;         acc[ai][bj][m][n] = __builtin_amdgcn_mfma_f32_16x16x32_bf16(Bt[n][k], At[m][k], acc[ai][bj][m][n], 0, 0, 0); __builtin_amdgcn_s_setprio(0); } while (0)
; #define PG8_WAIT_V(n) asm volatile("s_waitcnt vmcnt(" #n ")" ::: "memory")
; #define PG8_WAIT_L(n) asm volatile("s_waitcnt lgkmcnt(" #n ")" ::: "memory")
; template <class Epi, class Sched, bool ALIGN_EPI = false, bool SP2 = false>
; __device__ __forceinline__ void gemm_phase(PG8_LAS unsigned char* lds, const Gemm g, const Sched& S, const Epi& E, const int tid_in) {
;     ...
;             const bool last = (t == nt - 2);
;             const char* a1 = cA + (size_t)(t + 1) * kstep;
;             const char* a2 = last ? nA : cA + (size_t)(t + 2) * kstep; const char* b2 = last ? nB : cB + (size_t)(t + 2) * kstep;
;             const char* a3 = a2 + kstep; const char* b3 = b2 + kstep;
;             if (last && has_next) S.a_ready(nxt);
;             if constexpr (SP2) {
;             PG8_LDB(B0, 0, 0); PG8_LDB(B1, 0, 1); PG8_SCHED; PG8_LDA(At, 0, 0); PG8_STAGE(PG8_SA(1, 1), a1 + hstep, voffA);
;             PG8_WAIT_V(8); PG8_WAIT_L(0); PG8_BAR; PG8_MMA(0, 0, At, B0); PG8_MMA(0, 1, At, B1); PG8_BAR; PG8_SCHED;
;             PG8_LDA(At, 0, 1); PG8_STAGE(PG8_SB(0, 0), b2, voffB); PG8_STAGE(PG8_SB(0, 1), b2 + hstep, voffB); PG8_STAGE(PG8_SA(0, 0), a2, voffA);
;             PG8_WAIT_V(8); PG8_WAIT_L(0); PG8_BAR; PG8_MMA(1, 0, At, B0); PG8_MMA(1, 1, At, B1); PG8_BAR; PG8_SCHED;
.LBB0_197:
	s_add_u32 s51, s40, 0xfffc0080
	s_addc_u32 s56, s41, -1
	s_add_i32 s88, 0, 0x10000
	s_cmp_eq_u32 s49, 12
	s_cselect_b32 s59, s9, s56
	s_cselect_b32 s58, s16, s51
	s_cselect_b32 s57, s17, s39
	s_cselect_b32 s56, s20, s21
	s_add_i32 s51, 0, 0x14000
	v_add_u32_e32 v44, s88, v178
	v_add_u32_e32 v158, s51, v178
	ds_read_b128 v[24:27], v44
	ds_read_b128 v[28:31], v44 offset:1024
	ds_read_b128 v[40:43], v44 offset:2048
	ds_read_b128 v[44:47], v44 offset:3072
	ds_read_b128 v[154:157], v158
	ds_read_b128 v[182:185], v158 offset:1024
	ds_read_b128 v[186:189], v158 offset:2048
	ds_read_b128 v[190:193], v158 offset:3072
	v_lshl_add_u64 v[158:159], s[40:41], 0, v[150:151]
	s_add_i32 m0, s60, 0xc000
	ds_read_b128 v[194:197], v180
	ds_read_b128 v[198:201], v180 offset:1024
	ds_read_b128 v[202:205], v180 offset:2048
	ds_read_b128 v[206:209], v180 offset:3072
	ds_read_b128 v[210:213], v180 offset:4096
	ds_read_b128 v[214:217], v180 offset:5120
	ds_read_b128 v[218:221], v180 offset:6144
	ds_read_b128 v[238:241], v180 offset:7168
	global_load_lds_dwordx4 v[158:159], off
	v_lshl_add_u64 v[158:159], s[40:41], 0, v[152:153]
	s_add_i32 m0, s60, 0xe000
	s_nop 0
	global_load_lds_dwordx4 v[158:159], off
	s_waitcnt vmcnt(8)
	s_waitcnt lgkmcnt(0)
	s_barrier
	s_waitcnt lgkmcnt(0)
	v_mfma_f32_16x16x32_bf16 v[140:143], v[24:27], v[194:197], v[140:143]
	v_mfma_f32_16x16x32_bf16 v[136:139], v[40:43], v[194:197], v[136:139]
	v_mfma_f32_16x16x32_bf16 v[124:127], v[24:27], v[202:205], v[124:127]
	v_mfma_f32_16x16x32_bf16 v[120:123], v[40:43], v[202:205], v[120:123]
	v_mfma_f32_16x16x32_bf16 v[108:111], v[24:27], v[210:213], v[108:111]
	v_mfma_f32_16x16x32_bf16 v[104:107], v[40:43], v[210:213], v[104:107]
	v_mfma_f32_16x16x32_bf16 v[92:95], v[24:27], v[218:221], v[92:95]
	v_mfma_f32_16x16x32_bf16 v[88:91], v[40:43], v[218:221], v[88:91]
	v_mfma_f32_16x16x32_bf16 v[140:143], v[28:31], v[198:201], v[140:143]
	v_mfma_f32_16x16x32_bf16 v[136:139], v[44:47], v[198:201], v[136:139]
	v_mfma_f32_16x16x32_bf16 v[124:127], v[28:31], v[206:209], v[124:127]
	v_mfma_f32_16x16x32_bf16 v[120:123], v[44:47], v[206:209], v[120:123]
	v_mfma_f32_16x16x32_bf16 v[108:111], v[28:31], v[214:217], v[108:111]
	v_mfma_f32_16x16x32_bf16 v[104:107], v[44:47], v[214:217], v[104:107]
	v_mfma_f32_16x16x32_bf16 v[92:95], v[28:31], v[238:241], v[92:95]
	v_mfma_f32_16x16x32_bf16 v[88:91], v[44:47], v[238:241], v[88:91]
	v_mfma_f32_16x16x32_bf16 v[132:135], v[154:157], v[194:197], v[132:135]
	v_mfma_f32_16x16x32_bf16 v[128:131], v[186:189], v[194:197], v[128:131]
	v_mfma_f32_16x16x32_bf16 v[116:119], v[154:157], v[202:205], v[116:119]
	v_mfma_f32_16x16x32_bf16 v[112:115], v[186:189], v[202:205], v[112:115]
	v_mfma_f32_16x16x32_bf16 v[100:103], v[154:157], v[210:213], v[100:103]
	v_mfma_f32_16x16x32_bf16 v[96:99], v[186:189], v[210:213], v[96:99]
	v_mfma_f32_16x16x32_bf16 v[84:87], v[154:157], v[218:221], v[84:87]
	v_mfma_f32_16x16x32_bf16 v[80:83], v[186:189], v[218:221], v[80:83]
	v_mfma_f32_16x16x32_bf16 v[132:135], v[182:185], v[198:201], v[132:135]
	v_mfma_f32_16x16x32_bf16 v[128:131], v[190:193], v[198:201], v[128:131]
	v_mfma_f32_16x16x32_bf16 v[116:119], v[182:185], v[206:209], v[116:119]
	v_mfma_f32_16x16x32_bf16 v[112:115], v[190:193], v[206:209], v[112:115]
	v_mfma_f32_16x16x32_bf16 v[100:103], v[182:185], v[214:217], v[100:103]
	v_mfma_f32_16x16x32_bf16 v[96:99], v[190:193], v[214:217], v[96:99]
	v_mfma_f32_16x16x32_bf16 v[84:87], v[182:185], v[238:241], v[84:87]
	v_mfma_f32_16x16x32_bf16 v[80:83], v[190:193], v[238:241], v[80:83]
	s_barrier
	s_add_i32 s88, s88, s29
	v_lshl_add_u64 v[158:159], s[56:57], 0, v[160:161]
	s_mov_b32 m0, s88
	ds_read_b128 v[194:197], v180 offset:16384
	ds_read_b128 v[198:201], v180 offset:17408
	ds_read_b128 v[202:205], v180 offset:18432
	ds_read_b128 v[206:209], v180 offset:19456
	ds_read_b128 v[210:213], v180 offset:20480
	ds_read_b128 v[214:217], v180 offset:21504
	ds_read_b128 v[218:221], v180 offset:22528
	ds_read_b128 v[238:241], v180 offset:23552
	global_load_lds_dwordx4 v[158:159], off
	s_add_i32 m0, s88, 0x2000
	s_add_u32 s88, s56, 0x40000
	v_lshl_add_u64 v[176:177], s[56:57], 0, v[144:145]
	s_addc_u32 s89, s57, 0
	s_add_i32 s51, s51, s29
	global_load_lds_dwordx4 v[176:177], off
	v_lshl_add_u64 v[242:243], s[88:89], 0, v[160:161]
	s_mov_b32 m0, s51
	v_lshl_add_u64 v[244:245], s[58:59], 0, v[146:147]
	global_load_lds_dwordx4 v[242:243], off
	v_lshl_add_u64 v[242:243], s[88:89], 0, v[144:145]
	s_add_i32 m0, s51, 0x2000
	s_nop 0
	global_load_lds_dwordx4 v[242:243], off
	v_lshl_add_u64 v[242:243], s[58:59], 0, v[148:149]
	s_mov_b32 m0, s60
	s_nop 0
	global_load_lds_dwordx4 v[242:243], off
	s_mov_b32 m0, s61
	s_nop 0
	global_load_lds_dwordx4 v[244:245], off
	s_waitcnt vmcnt(8)
	s_waitcnt lgkmcnt(0)
	s_barrier
; #define PG8_STAGE(bufoff, gbase, voff) do { _Pragma("unroll") for (int _i = 0; _i < 2; ++_i) \
;         __builtin_amdgcn_global_load_lds((const unsigned*)((const char*)(gbase) + (voff)[_i]), (PG8_LAS unsigned*)(lds + (bufoff) + ldsw + _i * 8192), 16, 0, 0); } while (0)
; #define PG8_LDA(dst, b, h) do { _Pragma("unroll") for (int m = 0; m < 4; ++m) _Pragma("unroll") for (int k = 0; k < 2; ++k) dst[m][k] = *(const PG8_LAS bf16x8*)(lds + PG8_SA(b, h) + aoff + m * 2048 + k * 1024); } while (0)
; #define PG8_LDB(dst, b, h) do { _Pragma("unroll") for (int n = 0; n < 2; ++n) _Pragma("unroll") for (int k = 0; k < 2; ++k) dst[n][k] = *(const PG8_LAS bf16x8*)(lds + PG8_SB(b, h) + boff + n * 2048 + k * 1024); } while (0)
; #define PG8_MMA(ai, bj, At, Bt) do { __builtin_amdgcn_s_setprio(1); _Pragma("unroll") for (int m = 0; m < 4; ++m) _Pragma("unroll") for (int n = 0; n < 2; ++n) _Pragma("unroll") for (int k = 0; k < 2; ++k) \
;         acc[ai][bj][m][n] = __builtin_amdgcn_mfma_f32_16x16x32_bf16(Bt[n][k], At[m][k], acc[ai][bj][m][n], 0, 0, 0); __builtin_amdgcn_s_setprio(0); } while (0)
; #define PG8_WAIT_V(n) asm volatile("s_waitcnt vmcnt(" #n ")" ::: "memory")
; #define PG8_WAIT_L(n) asm volatile("s_waitcnt lgkmcnt(" #n ")" ::: "memory")
; #define PG8_BAR __builtin_amdgcn_s_barrier()
; #define PG8_SCHED __builtin_amdgcn_sched_barrier(0)
; template <class Epi, class Sched, bool ALIGN_EPI = false, bool SP2 = false>
; __device__ __forceinline__ void gemm_phase(PG8_LAS unsigned char* lds, const Gemm g, const Sched& S, const Epi& E, const int tid_in) {
;     ...
;             PG8_WAIT_V(8); PG8_WAIT_L(0); PG8_BAR; PG8_MMA(0, 0, At, B0); PG8_MMA(0, 1, At, B1); PG8_BAR; PG8_SCHED;
;             PG8_LDA(At, 0, 1); PG8_STAGE(PG8_SB(0, 0), b2, voffB); PG8_STAGE(PG8_SB(0, 1), b2 + hstep, voffB); PG8_STAGE(PG8_SA(0, 0), a2, voffA);
;             PG8_WAIT_V(8); PG8_WAIT_L(0); PG8_BAR; PG8_MMA(1, 0, At, B0); PG8_MMA(1, 1, At, B1); PG8_BAR; PG8_SCHED;
;             PG8_LDB(B0, 1, 0); PG8_LDB(B1, 1, 1); PG8_SCHED; PG8_LDA(At, 1, 0); PG8_STAGE(PG8_SA(0, 1), a2 + hstep, voffA);
;             PG8_WAIT_V(8); PG8_WAIT_L(0); PG8_BAR; PG8_MMA(0, 0, At, B0); PG8_MMA(0, 1, At, B1); PG8_BAR; PG8_SCHED;
	s_waitcnt lgkmcnt(0)
	v_mfma_f32_16x16x32_bf16 v[76:79], v[24:27], v[194:197], v[76:79]
	v_mfma_f32_16x16x32_bf16 v[72:75], v[40:43], v[194:197], v[72:75]
	v_mfma_f32_16x16x32_bf16 v[60:63], v[24:27], v[202:205], v[60:63]
	v_mfma_f32_16x16x32_bf16 v[56:59], v[40:43], v[202:205], v[56:59]
	v_mfma_f32_16x16x32_bf16 v[36:39], v[24:27], v[210:213], v[36:39]
	v_mfma_f32_16x16x32_bf16 v[32:35], v[40:43], v[210:213], v[32:35]
	v_mfma_f32_16x16x32_bf16 v[12:15], v[24:27], v[218:221], v[12:15]
	v_mfma_f32_16x16x32_bf16 v[8:11], v[40:43], v[218:221], v[8:11]
	v_mfma_f32_16x16x32_bf16 v[76:79], v[28:31], v[198:201], v[76:79]
	v_mfma_f32_16x16x32_bf16 v[72:75], v[44:47], v[198:201], v[72:75]
	v_mfma_f32_16x16x32_bf16 v[60:63], v[28:31], v[206:209], v[60:63]
	v_mfma_f32_16x16x32_bf16 v[56:59], v[44:47], v[206:209], v[56:59]
	v_mfma_f32_16x16x32_bf16 v[36:39], v[28:31], v[214:217], v[36:39]
	v_mfma_f32_16x16x32_bf16 v[32:35], v[44:47], v[214:217], v[32:35]
	v_mfma_f32_16x16x32_bf16 v[12:15], v[28:31], v[238:241], v[12:15]
	v_mfma_f32_16x16x32_bf16 v[8:11], v[44:47], v[238:241], v[8:11]
	v_mfma_f32_16x16x32_bf16 v[20:23], v[154:157], v[210:213], v[20:23]
	v_mfma_f32_16x16x32_bf16 v[16:19], v[186:189], v[210:213], v[16:19]
	v_mfma_f32_16x16x32_bf16 v[4:7], v[154:157], v[218:221], v[4:7]
	v_mfma_f32_16x16x32_bf16 v[0:3], v[186:189], v[218:221], v[0:3]
	v_mfma_f32_16x16x32_bf16 v[24:27], v[154:157], v[194:197], v[68:71]
	v_mfma_f32_16x16x32_bf16 v[28:31], v[186:189], v[194:197], v[64:67]
	v_mfma_f32_16x16x32_bf16 v[40:43], v[154:157], v[202:205], v[52:55]
	v_mfma_f32_16x16x32_bf16 v[44:47], v[186:189], v[202:205], v[48:51]
	v_mfma_f32_16x16x32_bf16 v[20:23], v[182:185], v[214:217], v[20:23]
	v_mfma_f32_16x16x32_bf16 v[16:19], v[190:193], v[214:217], v[16:19]
	v_mfma_f32_16x16x32_bf16 v[4:7], v[182:185], v[238:241], v[4:7]
	v_mfma_f32_16x16x32_bf16 v[0:3], v[190:193], v[238:241], v[0:3]
	v_mfma_f32_16x16x32_bf16 v[24:27], v[182:185], v[198:201], v[24:27]
	v_mfma_f32_16x16x32_bf16 v[28:31], v[190:193], v[198:201], v[28:31]
	v_mfma_f32_16x16x32_bf16 v[40:43], v[182:185], v[206:209], v[40:43]
	v_mfma_f32_16x16x32_bf16 v[44:47], v[190:193], v[206:209], v[44:47]
	s_barrier
	s_add_i32 s51, 0, 0x18000
	s_add_i32 s88, 0, 0x1c000
	v_add_u32_e32 v68, s51, v178
	v_add_u32_e32 v181, s88, v178
	ds_read_b128 v[48:51], v68
	ds_read_b128 v[52:55], v68 offset:1024
	ds_read_b128 v[64:67], v68 offset:2048
	ds_read_b128 v[68:71], v68 offset:3072
	ds_read_b128 v[154:157], v181
	ds_read_b128 v[182:185], v181 offset:1024
	ds_read_b128 v[186:189], v181 offset:2048
	ds_read_b128 v[190:193], v181 offset:3072
	s_add_u32 s58, s58, 0x40000
	s_addc_u32 s59, s59, 0
	s_mov_b32 m0, s62
	v_lshl_add_u64 v[246:247], s[58:59], 0, v[148:149]
	ds_read_b128 v[194:197], v180 offset:32768
	ds_read_b128 v[198:201], v180 offset:33792
	ds_read_b128 v[202:205], v180 offset:34816
	ds_read_b128 v[206:209], v180 offset:35840
	ds_read_b128 v[210:213], v180 offset:36864
	ds_read_b128 v[214:217], v180 offset:37888
	ds_read_b128 v[218:221], v180 offset:38912
	ds_read_b128 v[238:241], v180 offset:39936
	global_load_lds_dwordx4 v[246:247], off
	v_lshl_add_u64 v[246:247], s[58:59], 0, v[146:147]
	s_mov_b32 m0, s63
	s_nop 0
	global_load_lds_dwordx4 v[246:247], off
	s_waitcnt vmcnt(8)
	s_waitcnt lgkmcnt(0)
	s_barrier
	s_waitcnt lgkmcnt(0)
	v_mfma_f32_16x16x32_bf16 v[140:143], v[48:51], v[194:197], v[140:143]
	v_mfma_f32_16x16x32_bf16 v[136:139], v[64:67], v[194:197], v[136:139]
	v_mfma_f32_16x16x32_bf16 v[124:127], v[48:51], v[202:205], v[124:127]
	v_mfma_f32_16x16x32_bf16 v[120:123], v[64:67], v[202:205], v[120:123]
	v_mfma_f32_16x16x32_bf16 v[108:111], v[48:51], v[210:213], v[108:111]
	v_mfma_f32_16x16x32_bf16 v[104:107], v[64:67], v[210:213], v[104:107]
	v_mfma_f32_16x16x32_bf16 v[92:95], v[48:51], v[218:221], v[92:95]
	v_mfma_f32_16x16x32_bf16 v[88:91], v[64:67], v[218:221], v[88:91]
	v_mfma_f32_16x16x32_bf16 v[140:143], v[52:55], v[198:201], v[140:143]
	v_mfma_f32_16x16x32_bf16 v[136:139], v[68:71], v[198:201], v[136:139]
	v_mfma_f32_16x16x32_bf16 v[124:127], v[52:55], v[206:209], v[124:127]
	v_mfma_f32_16x16x32_bf16 v[120:123], v[68:71], v[206:209], v[120:123]
	v_mfma_f32_16x16x32_bf16 v[108:111], v[52:55], v[214:217], v[108:111]
	v_mfma_f32_16x16x32_bf16 v[104:107], v[68:71], v[214:217], v[104:107]
	v_mfma_f32_16x16x32_bf16 v[92:95], v[52:55], v[238:241], v[92:95]
	v_mfma_f32_16x16x32_bf16 v[88:91], v[68:71], v[238:241], v[88:91]
	v_mfma_f32_16x16x32_bf16 v[132:135], v[154:157], v[194:197], v[132:135]
	v_mfma_f32_16x16x32_bf16 v[128:131], v[186:189], v[194:197], v[128:131]
	v_mfma_f32_16x16x32_bf16 v[116:119], v[154:157], v[202:205], v[116:119]
	v_mfma_f32_16x16x32_bf16 v[112:115], v[186:189], v[202:205], v[112:115]
	v_mfma_f32_16x16x32_bf16 v[100:103], v[154:157], v[210:213], v[100:103]
	v_mfma_f32_16x16x32_bf16 v[96:99], v[186:189], v[210:213], v[96:99]
	v_mfma_f32_16x16x32_bf16 v[84:87], v[154:157], v[218:221], v[84:87]
	v_mfma_f32_16x16x32_bf16 v[80:83], v[186:189], v[218:221], v[80:83]
	v_mfma_f32_16x16x32_bf16 v[132:135], v[182:185], v[198:201], v[132:135]
	v_mfma_f32_16x16x32_bf16 v[128:131], v[190:193], v[198:201], v[128:131]
	v_mfma_f32_16x16x32_bf16 v[116:119], v[182:185], v[206:209], v[116:119]
	v_mfma_f32_16x16x32_bf16 v[112:115], v[190:193], v[206:209], v[112:115]
	v_mfma_f32_16x16x32_bf16 v[100:103], v[182:185], v[214:217], v[100:103]
	v_mfma_f32_16x16x32_bf16 v[96:99], v[190:193], v[214:217], v[96:99]
	v_mfma_f32_16x16x32_bf16 v[84:87], v[182:185], v[238:241], v[84:87]
	v_mfma_f32_16x16x32_bf16 v[80:83], v[190:193], v[238:241], v[80:83]
	s_barrier
; #define PG8_STAGE(bufoff, gbase, voff) do { _Pragma("unroll") for (int _i = 0; _i < 2; ++_i) \
;         __builtin_amdgcn_global_load_lds((const unsigned*)((const char*)(gbase) + (voff)[_i]), (PG8_LAS unsigned*)(lds + (bufoff) + ldsw + _i * 8192), 16, 0, 0); } while (0)
; #define PG8_LDA(dst, b, h) do { _Pragma("unroll") for (int m = 0; m < 4; ++m) _Pragma("unroll") for (int k = 0; k < 2; ++k) dst[m][k] = *(const PG8_LAS bf16x8*)(lds + PG8_SA(b, h) + aoff + m * 2048 + k * 1024); } while (0)
; #define PG8_MMA(ai, bj, At, Bt) do { __builtin_amdgcn_s_setprio(1); _Pragma("unroll") for (int m = 0; m < 4; ++m) _Pragma("unroll") for (int n = 0; n < 2; ++n) _Pragma("unroll") for (int k = 0; k < 2; ++k) \
;         acc[ai][bj][m][n] = __builtin_amdgcn_mfma_f32_16x16x32_bf16(Bt[n][k], At[m][k], acc[ai][bj][m][n], 0, 0, 0); __builtin_amdgcn_s_setprio(0); } while (0)
; #define PG8_WAIT_V(n) asm volatile("s_waitcnt vmcnt(" #n ")" ::: "memory")
; #define PG8_WAIT_L(n) asm volatile("s_waitcnt lgkmcnt(" #n ")" ::: "memory")
; #define PG8_BAR __builtin_amdgcn_s_barrier()
; #define PG8_SCHED __builtin_amdgcn_sched_barrier(0)
; template <class Epi, class Sched, bool ALIGN_EPI = false, bool SP2 = false>
; __device__ __forceinline__ void gemm_phase(PG8_LAS unsigned char* lds, const Gemm g, const Sched& S, const Epi& E, const int tid_in) {
;     ...
;             PG8_WAIT_V(8); PG8_WAIT_L(0); PG8_BAR; PG8_MMA(0, 0, At, B0); PG8_MMA(0, 1, At, B1); PG8_BAR; PG8_SCHED;
;             PG8_LDA(At, 1, 1); PG8_STAGE(PG8_SB(1, 0), b3, voffB); PG8_STAGE(PG8_SB(1, 1), b3 + hstep, voffB); PG8_STAGE(PG8_SA(1, 0), a3, voffA);
;             PG8_WAIT_V(8); PG8_WAIT_L(0); PG8_BAR; PG8_MMA(1, 0, At, B0); PG8_MMA(1, 1, At, B1); PG8_BAR; PG8_SCHED;
	s_add_i32 s51, s51, s29
	v_lshl_add_u64 v[158:159], v[158:159], 0, s[26:27]
	s_mov_b32 m0, s51
	ds_read_b128 v[194:197], v180 offset:49152
	ds_read_b128 v[198:201], v180 offset:50176
	ds_read_b128 v[202:205], v180 offset:51200
	ds_read_b128 v[206:209], v180 offset:52224
	ds_read_b128 v[210:213], v180 offset:53248
	ds_read_b128 v[214:217], v180 offset:54272
	ds_read_b128 v[218:221], v180 offset:55296
	ds_read_b128 v[238:241], v180 offset:56320
	global_load_lds_dwordx4 v[158:159], off
	s_add_i32 m0, s51, 0x2000
	s_add_u32 s56, s56, 0x40080
	v_lshl_add_u64 v[158:159], v[176:177], 0, s[26:27]
	s_addc_u32 s57, s57, 0
	s_add_i32 s51, s88, s29
	global_load_lds_dwordx4 v[158:159], off
	v_lshl_add_u64 v[158:159], s[56:57], 0, v[160:161]
	s_mov_b32 m0, s51
	s_nop 0
	global_load_lds_dwordx4 v[158:159], off
	v_lshl_add_u64 v[158:159], s[56:57], 0, v[144:145]
	s_add_i32 m0, s51, 0x2000
	s_nop 0
	global_load_lds_dwordx4 v[158:159], off
	v_lshl_add_u64 v[158:159], v[242:243], 0, s[26:27]
	s_mov_b32 m0, s84
	s_nop 0
	global_load_lds_dwordx4 v[158:159], off
	v_lshl_add_u64 v[158:159], v[244:245], 0, s[26:27]
	s_mov_b32 m0, s85
	s_nop 0
	global_load_lds_dwordx4 v[158:159], off
	s_waitcnt vmcnt(8)
	s_waitcnt lgkmcnt(0)
	s_barrier
	s_waitcnt lgkmcnt(0)
	v_mfma_f32_16x16x32_bf16 v[76:79], v[48:51], v[194:197], v[76:79]
	v_mfma_f32_16x16x32_bf16 v[72:75], v[64:67], v[194:197], v[72:75]
	v_mfma_f32_16x16x32_bf16 v[60:63], v[48:51], v[202:205], v[60:63]
	v_mfma_f32_16x16x32_bf16 v[56:59], v[64:67], v[202:205], v[56:59]
	v_mfma_f32_16x16x32_bf16 v[36:39], v[48:51], v[210:213], v[36:39]
	v_mfma_f32_16x16x32_bf16 v[32:35], v[64:67], v[210:213], v[32:35]
	v_mfma_f32_16x16x32_bf16 v[12:15], v[48:51], v[218:221], v[12:15]
	v_mfma_f32_16x16x32_bf16 v[8:11], v[64:67], v[218:221], v[8:11]
	v_mfma_f32_16x16x32_bf16 v[76:79], v[52:55], v[198:201], v[76:79]
	v_mfma_f32_16x16x32_bf16 v[72:75], v[68:71], v[198:201], v[72:75]
	v_mfma_f32_16x16x32_bf16 v[60:63], v[52:55], v[206:209], v[60:63]
	v_mfma_f32_16x16x32_bf16 v[56:59], v[68:71], v[206:209], v[56:59]
	v_mfma_f32_16x16x32_bf16 v[36:39], v[52:55], v[214:217], v[36:39]
	v_mfma_f32_16x16x32_bf16 v[32:35], v[68:71], v[214:217], v[32:35]
	v_mfma_f32_16x16x32_bf16 v[12:15], v[52:55], v[238:241], v[12:15]
	v_mfma_f32_16x16x32_bf16 v[8:11], v[68:71], v[238:241], v[8:11]
	v_mfma_f32_16x16x32_bf16 v[24:27], v[154:157], v[194:197], v[24:27]
	v_mfma_f32_16x16x32_bf16 v[68:71], v[182:185], v[198:201], v[24:27]
	v_mfma_f32_16x16x32_bf16 v[24:27], v[186:189], v[194:197], v[28:31]
	v_mfma_f32_16x16x32_bf16 v[64:67], v[190:193], v[198:201], v[24:27]
	v_mfma_f32_16x16x32_bf16 v[24:27], v[154:157], v[202:205], v[40:43]
	v_mfma_f32_16x16x32_bf16 v[52:55], v[182:185], v[206:209], v[24:27]
	v_mfma_f32_16x16x32_bf16 v[24:27], v[186:189], v[202:205], v[44:47]
	v_mfma_f32_16x16x32_bf16 v[20:23], v[154:157], v[210:213], v[20:23]
	v_mfma_f32_16x16x32_bf16 v[16:19], v[186:189], v[210:213], v[16:19]
	v_mfma_f32_16x16x32_bf16 v[4:7], v[154:157], v[218:221], v[4:7]
	v_mfma_f32_16x16x32_bf16 v[0:3], v[186:189], v[218:221], v[0:3]
	v_mfma_f32_16x16x32_bf16 v[48:51], v[190:193], v[206:209], v[24:27]
	v_mfma_f32_16x16x32_bf16 v[20:23], v[182:185], v[214:217], v[20:23]
	v_mfma_f32_16x16x32_bf16 v[16:19], v[190:193], v[214:217], v[16:19]
	v_mfma_f32_16x16x32_bf16 v[4:7], v[182:185], v[238:241], v[4:7]
	v_mfma_f32_16x16x32_bf16 v[0:3], v[190:193], v[238:241], v[0:3]
	s_barrier
	s_add_i32 s49, s49, 2
	s_add_u32 s40, s40, 0x100
	s_addc_u32 s41, s41, 0
	s_add_u32 s21, s21, 0x100
	s_addc_u32 s39, s39, 0
	s_cmp_gt_u32 s49, 13
	s_cbranch_scc0 .LBB0_197
	s_and_b64 vcc, exec, s[46:47]
	s_cbranch_vccz .LBB0_200
	s_barrier

; #define PG8_STAGE(bufoff, gbase, voff) do { _Pragma("unroll") for (int _i = 0; _i < 2; ++_i) \
;         __builtin_amdgcn_global_load_lds((const unsigned*)((const char*)(gbase) + (voff)[_i]), (PG8_LAS unsigned*)(lds + (bufoff) + ldsw + _i * 8192), 16, 0, 0); } while (0)
; #define PG8_LDA(dst, b, h) do { _Pragma("unroll") for (int m = 0; m < 4; ++m) _Pragma("unroll") for (int k = 0; k < 2; ++k) dst[m][k] = *(const PG8_LAS bf16x8*)(lds + PG8_SA(b, h) + aoff + m * 2048 + k * 1024); } while (0)
; #define PG8_LDB(dst, b, h) do { _Pragma("unroll") for (int n = 0; n < 2; ++n) _Pragma("unroll") for (int k = 0; k < 2; ++k) dst[n][k] = *(const PG8_LAS bf16x8*)(lds + PG8_SB(b, h) + boff + n * 2048 + k * 1024); } while (0)
; #define PG8_MMA(ai, bj, At, Bt) do { __builtin_amdgcn_s_setprio(1); _Pragma("unroll") for (int m = 0; m < 4; ++m) _Pragma("unroll") for (int n = 0; n < 2; ++n) _Pragma("unroll") for (int k = 0; k < 2; ++k) \
;         acc[ai][bj][m][n] = __builtin_amdgcn_mfma_f32_16x16x32_bf16(Bt[n][k], At[m][k], acc[ai][bj][m][n], 0, 0, 0); __builtin_amdgcn_s_setprio(0); } while (0)
; #define PG8_WAIT_V(n) asm volatile("s_waitcnt vmcnt(" #n ")" ::: "memory")
; #define PG8_WAIT_L(n) asm volatile("s_waitcnt lgkmcnt(" #n ")" ::: "memory")
; template <class Epi, class Sched, bool ALIGN_EPI = false, bool SP2 = false>
; __device__ __forceinline__ void gemm_phase(PG8_LAS unsigned char* lds, const Gemm g, const Sched& S, const Epi& E, const int tid_in) {
;     ...
;             const bool last = (t == nt - 2);
;             const char* a1 = cA + (size_t)(t + 1) * kstep;
;             const char* a2 = last ? nA : cA + (size_t)(t + 2) * kstep; const char* b2 = last ? nB : cB + (size_t)(t + 2) * kstep;
;             const char* a3 = a2 + kstep; const char* b3 = b2 + kstep;
;             if (last && has_next) S.a_ready(nxt);
;             if constexpr (SP2) {
;             PG8_LDB(B0, 0, 0); PG8_LDB(B1, 0, 1); PG8_SCHED; PG8_LDA(At, 0, 0); PG8_STAGE(PG8_SA(1, 1), a1 + hstep, voffA);
;             PG8_WAIT_V(8); PG8_WAIT_L(0); PG8_BAR; PG8_MMA(0, 0, At, B0); PG8_MMA(0, 1, At, B1); PG8_BAR; PG8_SCHED;
;             PG8_LDA(At, 0, 1); PG8_STAGE(PG8_SB(0, 0), b2, voffB); PG8_STAGE(PG8_SB(0, 1), b2 + hstep, voffB); PG8_STAGE(PG8_SA(0, 0), a2, voffA);
;             PG8_WAIT_V(8); PG8_WAIT_L(0); PG8_BAR; PG8_MMA(1, 0, At, B0); PG8_MMA(1, 1, At, B1); PG8_BAR; PG8_SCHED;
.LBB0_322:
	s_add_i32 s65, s46, 2
	s_add_u32 vcc_lo, s40, 0x80
	s_addc_u32 s47, s41, 0
	s_add_i32 s10, 0, 0x10000
	s_cmp_eq_u32 s93, s46
	s_cselect_b32 s47, s61, s47
	s_cselect_b32 s46, s60, vcc_lo
	s_cselect_b32 vcc_hi, s63, s64
	s_cselect_b32 vcc_lo, s62, s21
	s_add_i32 s11, 0, 0x14000
	v_add_u32_e32 v140, s10, v237
	v_add_u32_e32 v156, s11, v237
	ds_read_b128 v[128:131], v140
	ds_read_b128 v[132:135], v140 offset:1024
	ds_read_b128 v[136:139], v140 offset:2048
	ds_read_b128 v[140:143], v140 offset:3072
	ds_read_b128 v[144:147], v156
	ds_read_b128 v[148:151], v156 offset:1024
	ds_read_b128 v[152:155], v156 offset:2048
	ds_read_b128 v[156:159], v156 offset:3072
	v_lshl_add_u64 v[240:241], s[40:41], 0, v[186:187]
	s_add_i32 m0, s88, 0xc000
	ds_read_b128 v[190:193], v239
	ds_read_b128 v[194:197], v239 offset:1024
	ds_read_b128 v[198:201], v239 offset:2048
	ds_read_b128 v[202:205], v239 offset:3072
	ds_read_b128 v[206:209], v239 offset:4096
	ds_read_b128 v[210:213], v239 offset:5120
	ds_read_b128 v[214:217], v239 offset:6144
	ds_read_b128 v[218:221], v239 offset:7168
	global_load_lds_dwordx4 v[240:241], off
	v_lshl_add_u64 v[240:241], s[40:41], 0, v[188:189]
	s_add_i32 m0, s88, 0xe000
	s_nop 0
	global_load_lds_dwordx4 v[240:241], off
	s_waitcnt vmcnt(8)
	s_waitcnt lgkmcnt(0)
	s_barrier
	s_waitcnt lgkmcnt(0)
	v_mfma_f32_16x16x32_bf16 v[124:127], v[128:131], v[190:193], v[124:127]
	v_mfma_f32_16x16x32_bf16 v[120:123], v[136:139], v[190:193], v[120:123]
	v_mfma_f32_16x16x32_bf16 v[108:111], v[128:131], v[198:201], v[108:111]
	v_mfma_f32_16x16x32_bf16 v[104:107], v[136:139], v[198:201], v[104:107]
	v_mfma_f32_16x16x32_bf16 v[92:95], v[128:131], v[206:209], v[92:95]
	v_mfma_f32_16x16x32_bf16 v[88:91], v[136:139], v[206:209], v[88:91]
	v_mfma_f32_16x16x32_bf16 v[76:79], v[128:131], v[214:217], v[76:79]
	v_mfma_f32_16x16x32_bf16 v[72:75], v[136:139], v[214:217], v[72:75]
	v_mfma_f32_16x16x32_bf16 v[124:127], v[132:135], v[194:197], v[124:127]
	v_mfma_f32_16x16x32_bf16 v[120:123], v[140:143], v[194:197], v[120:123]
	v_mfma_f32_16x16x32_bf16 v[108:111], v[132:135], v[202:205], v[108:111]
	v_mfma_f32_16x16x32_bf16 v[104:107], v[140:143], v[202:205], v[104:107]
	v_mfma_f32_16x16x32_bf16 v[92:95], v[132:135], v[210:213], v[92:95]
	v_mfma_f32_16x16x32_bf16 v[88:91], v[140:143], v[210:213], v[88:91]
	v_mfma_f32_16x16x32_bf16 v[76:79], v[132:135], v[218:221], v[76:79]
	v_mfma_f32_16x16x32_bf16 v[72:75], v[140:143], v[218:221], v[72:75]
	v_mfma_f32_16x16x32_bf16 v[116:119], v[144:147], v[190:193], v[116:119]
	v_mfma_f32_16x16x32_bf16 v[112:115], v[152:155], v[190:193], v[112:115]
	v_mfma_f32_16x16x32_bf16 v[100:103], v[144:147], v[198:201], v[100:103]
	v_mfma_f32_16x16x32_bf16 v[96:99], v[152:155], v[198:201], v[96:99]
	v_mfma_f32_16x16x32_bf16 v[84:87], v[144:147], v[206:209], v[84:87]
	v_mfma_f32_16x16x32_bf16 v[80:83], v[152:155], v[206:209], v[80:83]
	v_mfma_f32_16x16x32_bf16 v[68:71], v[144:147], v[214:217], v[68:71]
	v_mfma_f32_16x16x32_bf16 v[64:67], v[152:155], v[214:217], v[64:67]
	v_mfma_f32_16x16x32_bf16 v[116:119], v[148:151], v[194:197], v[116:119]
	v_mfma_f32_16x16x32_bf16 v[112:115], v[156:159], v[194:197], v[112:115]
	v_mfma_f32_16x16x32_bf16 v[100:103], v[148:151], v[202:205], v[100:103]
	v_mfma_f32_16x16x32_bf16 v[96:99], v[156:159], v[202:205], v[96:99]
	v_mfma_f32_16x16x32_bf16 v[84:87], v[148:151], v[210:213], v[84:87]
	v_mfma_f32_16x16x32_bf16 v[80:83], v[156:159], v[210:213], v[80:83]
	v_mfma_f32_16x16x32_bf16 v[68:71], v[148:151], v[218:221], v[68:71]
	v_mfma_f32_16x16x32_bf16 v[64:67], v[156:159], v[218:221], v[64:67]
	s_barrier
	s_add_i32 s10, s10, s87
	v_lshl_add_u64 v[240:241], vcc, 0, v[160:161]
	s_mov_b32 m0, s10
	ds_read_b128 v[190:193], v239 offset:16384
	ds_read_b128 v[194:197], v239 offset:17408
	ds_read_b128 v[198:201], v239 offset:18432
	ds_read_b128 v[202:205], v239 offset:19456
	ds_read_b128 v[206:209], v239 offset:20480
	ds_read_b128 v[210:213], v239 offset:21504
	ds_read_b128 v[214:217], v239 offset:22528
	ds_read_b128 v[218:221], v239 offset:23552
	global_load_lds_dwordx4 v[240:241], off
	s_add_i32 m0, s10, 0x2000
	v_lshl_add_u64 v[242:243], vcc, 0, v[176:177]
	s_add_u32 vcc_lo, vcc_lo, s22
	s_addc_u32 vcc_hi, vcc_hi, 0
	s_add_i32 s10, s11, s87
	global_load_lds_dwordx4 v[242:243], off
	v_lshl_add_u64 v[244:245], vcc, 0, v[160:161]
	s_mov_b32 m0, s10
	v_lshl_add_u64 v[246:247], vcc, 0, v[176:177]
	global_load_lds_dwordx4 v[244:245], off
	s_add_i32 m0, s10, 0x2000
	v_lshl_add_u64 v[248:249], s[46:47], 0, v[180:181]
	global_load_lds_dwordx4 v[246:247], off
	s_mov_b32 m0, s88
	v_lshl_add_u64 v[250:251], s[46:47], 0, v[178:179]
	global_load_lds_dwordx4 v[248:249], off
	s_mov_b32 m0, s89
	s_nop 0
	global_load_lds_dwordx4 v[250:251], off
	s_waitcnt vmcnt(8)
	s_waitcnt lgkmcnt(0)
	s_barrier
; #define PG8_STAGE(bufoff, gbase, voff) do { _Pragma("unroll") for (int _i = 0; _i < 2; ++_i) \
;         __builtin_amdgcn_global_load_lds((const unsigned*)((const char*)(gbase) + (voff)[_i]), (PG8_LAS unsigned*)(lds + (bufoff) + ldsw + _i * 8192), 16, 0, 0); } while (0)
; #define PG8_LDA(dst, b, h) do { _Pragma("unroll") for (int m = 0; m < 4; ++m) _Pragma("unroll") for (int k = 0; k < 2; ++k) dst[m][k] = *(const PG8_LAS bf16x8*)(lds + PG8_SA(b, h) + aoff + m * 2048 + k * 1024); } while (0)
; #define PG8_LDB(dst, b, h) do { _Pragma("unroll") for (int n = 0; n < 2; ++n) _Pragma("unroll") for (int k = 0; k < 2; ++k) dst[n][k] = *(const PG8_LAS bf16x8*)(lds + PG8_SB(b, h) + boff + n * 2048 + k * 1024); } while (0)
; #define PG8_MMA(ai, bj, At, Bt) do { __builtin_amdgcn_s_setprio(1); _Pragma("unroll") for (int m = 0; m < 4; ++m) _Pragma("unroll") for (int n = 0; n < 2; ++n) _Pragma("unroll") for (int k = 0; k < 2; ++k) \
;         acc[ai][bj][m][n] = __builtin_amdgcn_mfma_f32_16x16x32_bf16(Bt[n][k], At[m][k], acc[ai][bj][m][n], 0, 0, 0); __builtin_amdgcn_s_setprio(0); } while (0)
; #define PG8_WAIT_V(n) asm volatile("s_waitcnt vmcnt(" #n ")" ::: "memory")
; #define PG8_WAIT_L(n) asm volatile("s_waitcnt lgkmcnt(" #n ")" ::: "memory")
; #define PG8_BAR __builtin_amdgcn_s_barrier()
; #define PG8_SCHED __builtin_amdgcn_sched_barrier(0)
; template <class Epi, class Sched, bool ALIGN_EPI = false, bool SP2 = false>
; __device__ __forceinline__ void gemm_phase(PG8_LAS unsigned char* lds, const Gemm g, const Sched& S, const Epi& E, const int tid_in) {
;     ...
;             PG8_WAIT_V(8); PG8_WAIT_L(0); PG8_BAR; PG8_MMA(0, 0, At, B0); PG8_MMA(0, 1, At, B1); PG8_BAR; PG8_SCHED;
;             PG8_LDA(At, 0, 1); PG8_STAGE(PG8_SB(0, 0), b2, voffB); PG8_STAGE(PG8_SB(0, 1), b2 + hstep, voffB); PG8_STAGE(PG8_SA(0, 0), a2, voffA);
;             PG8_WAIT_V(8); PG8_WAIT_L(0); PG8_BAR; PG8_MMA(1, 0, At, B0); PG8_MMA(1, 1, At, B1); PG8_BAR; PG8_SCHED;
;             PG8_LDB(B0, 1, 0); PG8_LDB(B1, 1, 1); PG8_SCHED; PG8_LDA(At, 1, 0); PG8_STAGE(PG8_SA(0, 1), a2 + hstep, voffA);
;             PG8_WAIT_V(8); PG8_WAIT_L(0); PG8_BAR; PG8_MMA(0, 0, At, B0); PG8_MMA(0, 1, At, B1); PG8_BAR; PG8_SCHED;
	s_waitcnt lgkmcnt(0)
	v_mfma_f32_16x16x32_bf16 v[60:63], v[128:131], v[190:193], v[60:63]
	v_mfma_f32_16x16x32_bf16 v[56:59], v[136:139], v[190:193], v[56:59]
	v_mfma_f32_16x16x32_bf16 v[44:47], v[128:131], v[198:201], v[44:47]
	v_mfma_f32_16x16x32_bf16 v[40:43], v[136:139], v[198:201], v[40:43]
	v_mfma_f32_16x16x32_bf16 v[28:31], v[128:131], v[206:209], v[28:31]
	v_mfma_f32_16x16x32_bf16 v[24:27], v[136:139], v[206:209], v[24:27]
	v_mfma_f32_16x16x32_bf16 v[12:15], v[128:131], v[214:217], v[12:15]
	v_mfma_f32_16x16x32_bf16 v[8:11], v[136:139], v[214:217], v[8:11]
	v_mfma_f32_16x16x32_bf16 v[60:63], v[132:135], v[194:197], v[60:63]
	v_mfma_f32_16x16x32_bf16 v[56:59], v[140:143], v[194:197], v[56:59]
	v_mfma_f32_16x16x32_bf16 v[44:47], v[132:135], v[202:205], v[44:47]
	v_mfma_f32_16x16x32_bf16 v[40:43], v[140:143], v[202:205], v[40:43]
	v_mfma_f32_16x16x32_bf16 v[28:31], v[132:135], v[210:213], v[28:31]
	v_mfma_f32_16x16x32_bf16 v[24:27], v[140:143], v[210:213], v[24:27]
	v_mfma_f32_16x16x32_bf16 v[12:15], v[132:135], v[218:221], v[12:15]
	v_mfma_f32_16x16x32_bf16 v[8:11], v[140:143], v[218:221], v[8:11]
	v_mfma_f32_16x16x32_bf16 v[52:55], v[144:147], v[190:193], v[52:55]
	v_mfma_f32_16x16x32_bf16 v[48:51], v[152:155], v[190:193], v[48:51]
	v_mfma_f32_16x16x32_bf16 v[36:39], v[144:147], v[198:201], v[36:39]
	v_mfma_f32_16x16x32_bf16 v[32:35], v[152:155], v[198:201], v[32:35]
	v_mfma_f32_16x16x32_bf16 v[20:23], v[144:147], v[206:209], v[20:23]
	v_mfma_f32_16x16x32_bf16 v[16:19], v[152:155], v[206:209], v[16:19]
	v_mfma_f32_16x16x32_bf16 v[4:7], v[144:147], v[214:217], v[4:7]
	v_mfma_f32_16x16x32_bf16 v[0:3], v[152:155], v[214:217], v[0:3]
	v_mfma_f32_16x16x32_bf16 v[52:55], v[148:151], v[194:197], v[52:55]
	v_mfma_f32_16x16x32_bf16 v[48:51], v[156:159], v[194:197], v[48:51]
	v_mfma_f32_16x16x32_bf16 v[36:39], v[148:151], v[202:205], v[36:39]
	v_mfma_f32_16x16x32_bf16 v[32:35], v[156:159], v[202:205], v[32:35]
	v_mfma_f32_16x16x32_bf16 v[20:23], v[148:151], v[210:213], v[20:23]
	v_mfma_f32_16x16x32_bf16 v[16:19], v[156:159], v[210:213], v[16:19]
	v_mfma_f32_16x16x32_bf16 v[4:7], v[148:151], v[218:221], v[4:7]
	v_mfma_f32_16x16x32_bf16 v[0:3], v[156:159], v[218:221], v[0:3]
	s_barrier
	s_add_i32 s10, 0, 0x18000
	s_add_i32 s11, 0, 0x1c000
	v_add_u32_e32 v140, s10, v237
	v_add_u32_e32 v156, s11, v237
	ds_read_b128 v[128:131], v140
	ds_read_b128 v[132:135], v140 offset:1024
	ds_read_b128 v[136:139], v140 offset:2048
	ds_read_b128 v[140:143], v140 offset:3072
	ds_read_b128 v[144:147], v156
	ds_read_b128 v[148:151], v156 offset:1024
	ds_read_b128 v[152:155], v156 offset:2048
	ds_read_b128 v[156:159], v156 offset:3072
	s_add_u32 s46, s46, s22
	s_addc_u32 s47, s47, 0
	s_mov_b32 m0, s90
	v_lshl_add_u64 v[232:233], s[46:47], 0, v[180:181]
	ds_read_b128 v[190:193], v239 offset:32768
	ds_read_b128 v[194:197], v239 offset:33792
	ds_read_b128 v[198:201], v239 offset:34816
	ds_read_b128 v[202:205], v239 offset:35840
	ds_read_b128 v[206:209], v239 offset:36864
	ds_read_b128 v[210:213], v239 offset:37888
	ds_read_b128 v[214:217], v239 offset:38912
	ds_read_b128 v[218:221], v239 offset:39936
	global_load_lds_dwordx4 v[232:233], off
	v_lshl_add_u64 v[232:233], s[46:47], 0, v[178:179]
	s_mov_b32 m0, s91
	s_nop 0
	global_load_lds_dwordx4 v[232:233], off
	s_waitcnt vmcnt(8)
	s_waitcnt lgkmcnt(0)
	s_barrier
	s_waitcnt lgkmcnt(0)
	v_mfma_f32_16x16x32_bf16 v[124:127], v[128:131], v[190:193], v[124:127]
	v_mfma_f32_16x16x32_bf16 v[120:123], v[136:139], v[190:193], v[120:123]
	v_mfma_f32_16x16x32_bf16 v[108:111], v[128:131], v[198:201], v[108:111]
	v_mfma_f32_16x16x32_bf16 v[104:107], v[136:139], v[198:201], v[104:107]
	v_mfma_f32_16x16x32_bf16 v[92:95], v[128:131], v[206:209], v[92:95]
	v_mfma_f32_16x16x32_bf16 v[88:91], v[136:139], v[206:209], v[88:91]
	v_mfma_f32_16x16x32_bf16 v[76:79], v[128:131], v[214:217], v[76:79]
	v_mfma_f32_16x16x32_bf16 v[72:75], v[136:139], v[214:217], v[72:75]
	v_mfma_f32_16x16x32_bf16 v[124:127], v[132:135], v[194:197], v[124:127]
	v_mfma_f32_16x16x32_bf16 v[120:123], v[140:143], v[194:197], v[120:123]
	v_mfma_f32_16x16x32_bf16 v[108:111], v[132:135], v[202:205], v[108:111]
	v_mfma_f32_16x16x32_bf16 v[104:107], v[140:143], v[202:205], v[104:107]
	v_mfma_f32_16x16x32_bf16 v[92:95], v[132:135], v[210:213], v[92:95]
	v_mfma_f32_16x16x32_bf16 v[88:91], v[140:143], v[210:213], v[88:91]
	v_mfma_f32_16x16x32_bf16 v[76:79], v[132:135], v[218:221], v[76:79]
	v_mfma_f32_16x16x32_bf16 v[72:75], v[140:143], v[218:221], v[72:75]
	v_mfma_f32_16x16x32_bf16 v[116:119], v[144:147], v[190:193], v[116:119]
	v_mfma_f32_16x16x32_bf16 v[112:115], v[152:155], v[190:193], v[112:115]
	v_mfma_f32_16x16x32_bf16 v[100:103], v[144:147], v[198:201], v[100:103]
	v_mfma_f32_16x16x32_bf16 v[96:99], v[152:155], v[198:201], v[96:99]
	v_mfma_f32_16x16x32_bf16 v[84:87], v[144:147], v[206:209], v[84:87]
	v_mfma_f32_16x16x32_bf16 v[80:83], v[152:155], v[206:209], v[80:83]
	v_mfma_f32_16x16x32_bf16 v[68:71], v[144:147], v[214:217], v[68:71]
	v_mfma_f32_16x16x32_bf16 v[64:67], v[152:155], v[214:217], v[64:67]
	v_mfma_f32_16x16x32_bf16 v[116:119], v[148:151], v[194:197], v[116:119]
	v_mfma_f32_16x16x32_bf16 v[112:115], v[156:159], v[194:197], v[112:115]
	v_mfma_f32_16x16x32_bf16 v[100:103], v[148:151], v[202:205], v[100:103]
	v_mfma_f32_16x16x32_bf16 v[96:99], v[156:159], v[202:205], v[96:99]
	v_mfma_f32_16x16x32_bf16 v[84:87], v[148:151], v[210:213], v[84:87]
	v_mfma_f32_16x16x32_bf16 v[80:83], v[156:159], v[210:213], v[80:83]
	v_mfma_f32_16x16x32_bf16 v[68:71], v[148:151], v[218:221], v[68:71]
	v_mfma_f32_16x16x32_bf16 v[64:67], v[156:159], v[218:221], v[64:67]
	s_barrier
; #define PG8_STAGE(bufoff, gbase, voff) do { _Pragma("unroll") for (int _i = 0; _i < 2; ++_i) \
;         __builtin_amdgcn_global_load_lds((const unsigned*)((const char*)(gbase) + (voff)[_i]), (PG8_LAS unsigned*)(lds + (bufoff) + ldsw + _i * 8192), 16, 0, 0); } while (0)
; #define PG8_LDA(dst, b, h) do { _Pragma("unroll") for (int m = 0; m < 4; ++m) _Pragma("unroll") for (int k = 0; k < 2; ++k) dst[m][k] = *(const PG8_LAS bf16x8*)(lds + PG8_SA(b, h) + aoff + m * 2048 + k * 1024); } while (0)
; #define PG8_MMA(ai, bj, At, Bt) do { __builtin_amdgcn_s_setprio(1); _Pragma("unroll") for (int m = 0; m < 4; ++m) _Pragma("unroll") for (int n = 0; n < 2; ++n) _Pragma("unroll") for (int k = 0; k < 2; ++k) \
;         acc[ai][bj][m][n] = __builtin_amdgcn_mfma_f32_16x16x32_bf16(Bt[n][k], At[m][k], acc[ai][bj][m][n], 0, 0, 0); __builtin_amdgcn_s_setprio(0); } while (0)
; #define PG8_WAIT_V(n) asm volatile("s_waitcnt vmcnt(" #n ")" ::: "memory")
; #define PG8_WAIT_L(n) asm volatile("s_waitcnt lgkmcnt(" #n ")" ::: "memory")
; #define PG8_BAR __builtin_amdgcn_s_barrier()
; #define PG8_SCHED __builtin_amdgcn_sched_barrier(0)
; template <class Epi, class Sched, bool ALIGN_EPI = false, bool SP2 = false>
; __device__ __forceinline__ void gemm_phase(PG8_LAS unsigned char* lds, const Gemm g, const Sched& S, const Epi& E, const int tid_in) {
;     ...
;             PG8_WAIT_V(8); PG8_WAIT_L(0); PG8_BAR; PG8_MMA(0, 0, At, B0); PG8_MMA(0, 1, At, B1); PG8_BAR; PG8_SCHED;
;             PG8_LDA(At, 1, 1); PG8_STAGE(PG8_SB(1, 0), b3, voffB); PG8_STAGE(PG8_SB(1, 1), b3 + hstep, voffB); PG8_STAGE(PG8_SA(1, 0), a3, voffA);
;             PG8_WAIT_V(8); PG8_WAIT_L(0); PG8_BAR; PG8_MMA(1, 0, At, B0); PG8_MMA(1, 1, At, B1); PG8_BAR; PG8_SCHED;
	s_add_i32 s10, s10, s87
	v_lshl_add_u64 v[232:233], v[240:241], 0, s[26:27]
	s_mov_b32 m0, s10
	ds_read_b128 v[190:193], v239 offset:49152
	ds_read_b128 v[194:197], v239 offset:50176
	ds_read_b128 v[198:201], v239 offset:51200
	ds_read_b128 v[202:205], v239 offset:52224
	ds_read_b128 v[206:209], v239 offset:53248
	ds_read_b128 v[210:213], v239 offset:54272
	ds_read_b128 v[214:217], v239 offset:55296
	ds_read_b128 v[218:221], v239 offset:56320
	global_load_lds_dwordx4 v[232:233], off
	v_lshl_add_u64 v[232:233], v[242:243], 0, s[26:27]
	s_add_i32 m0, s10, 0x2000
	s_add_i32 s10, s11, s87
	global_load_lds_dwordx4 v[232:233], off
	v_lshl_add_u64 v[232:233], v[244:245], 0, s[26:27]
	s_mov_b32 m0, s10
	s_nop 0
	global_load_lds_dwordx4 v[232:233], off
	v_lshl_add_u64 v[232:233], v[246:247], 0, s[26:27]
	s_add_i32 m0, s10, 0x2000
	s_nop 0
	global_load_lds_dwordx4 v[232:233], off
	v_lshl_add_u64 v[232:233], v[248:249], 0, s[26:27]
	s_mov_b32 m0, s94
	s_nop 0
	global_load_lds_dwordx4 v[232:233], off
	v_lshl_add_u64 v[232:233], v[250:251], 0, s[26:27]
	s_mov_b32 m0, s96
	s_nop 0
	global_load_lds_dwordx4 v[232:233], off
	s_waitcnt vmcnt(8)
	s_waitcnt lgkmcnt(0)
	s_barrier
	s_waitcnt lgkmcnt(0)
	v_mfma_f32_16x16x32_bf16 v[60:63], v[128:131], v[190:193], v[60:63]
	v_mfma_f32_16x16x32_bf16 v[56:59], v[136:139], v[190:193], v[56:59]
	v_mfma_f32_16x16x32_bf16 v[44:47], v[128:131], v[198:201], v[44:47]
	v_mfma_f32_16x16x32_bf16 v[40:43], v[136:139], v[198:201], v[40:43]
	v_mfma_f32_16x16x32_bf16 v[28:31], v[128:131], v[206:209], v[28:31]
	v_mfma_f32_16x16x32_bf16 v[24:27], v[136:139], v[206:209], v[24:27]
	v_mfma_f32_16x16x32_bf16 v[12:15], v[128:131], v[214:217], v[12:15]
	v_mfma_f32_16x16x32_bf16 v[8:11], v[136:139], v[214:217], v[8:11]
	v_mfma_f32_16x16x32_bf16 v[60:63], v[132:135], v[194:197], v[60:63]
	v_mfma_f32_16x16x32_bf16 v[56:59], v[140:143], v[194:197], v[56:59]
	v_mfma_f32_16x16x32_bf16 v[44:47], v[132:135], v[202:205], v[44:47]
	v_mfma_f32_16x16x32_bf16 v[40:43], v[140:143], v[202:205], v[40:43]
	v_mfma_f32_16x16x32_bf16 v[28:31], v[132:135], v[210:213], v[28:31]
	v_mfma_f32_16x16x32_bf16 v[24:27], v[140:143], v[210:213], v[24:27]
	v_mfma_f32_16x16x32_bf16 v[12:15], v[132:135], v[218:221], v[12:15]
	v_mfma_f32_16x16x32_bf16 v[8:11], v[140:143], v[218:221], v[8:11]
	v_mfma_f32_16x16x32_bf16 v[52:55], v[144:147], v[190:193], v[52:55]
	v_mfma_f32_16x16x32_bf16 v[48:51], v[152:155], v[190:193], v[48:51]
	v_mfma_f32_16x16x32_bf16 v[36:39], v[144:147], v[198:201], v[36:39]
	v_mfma_f32_16x16x32_bf16 v[32:35], v[152:155], v[198:201], v[32:35]
	v_mfma_f32_16x16x32_bf16 v[20:23], v[144:147], v[206:209], v[20:23]
	v_mfma_f32_16x16x32_bf16 v[16:19], v[152:155], v[206:209], v[16:19]
	v_mfma_f32_16x16x32_bf16 v[4:7], v[144:147], v[214:217], v[4:7]
	v_mfma_f32_16x16x32_bf16 v[0:3], v[152:155], v[214:217], v[0:3]
	v_mfma_f32_16x16x32_bf16 v[52:55], v[148:151], v[194:197], v[52:55]
	v_mfma_f32_16x16x32_bf16 v[48:51], v[156:159], v[194:197], v[48:51]
	v_mfma_f32_16x16x32_bf16 v[36:39], v[148:151], v[202:205], v[36:39]
	v_mfma_f32_16x16x32_bf16 v[32:35], v[156:159], v[202:205], v[32:35]
	v_mfma_f32_16x16x32_bf16 v[20:23], v[148:151], v[210:213], v[20:23]
	v_mfma_f32_16x16x32_bf16 v[16:19], v[156:159], v[210:213], v[16:19]
	v_mfma_f32_16x16x32_bf16 v[4:7], v[148:151], v[218:221], v[4:7]
	v_mfma_f32_16x16x32_bf16 v[0:3], v[156:159], v[218:221], v[0:3]
	s_barrier
	s_add_u32 s40, s40, 0x100
	s_addc_u32 s41, s41, 0
	s_add_u32 s21, s21, 0x100
	s_addc_u32 s64, s64, 0
	s_cmp_ge_u32 s65, s98
	s_mov_b32 s46, s65
	s_cbranch_scc0 .LBB0_322
	s_and_b64 vcc, exec, s[48:49]
	s_cbranch_vccz .LBB0_325
	s_barrier

; #define PG8_STAGE(bufoff, gbase, voff) do { _Pragma("unroll") for (int _i = 0; _i < 2; ++_i) \
;         __builtin_amdgcn_global_load_lds((const unsigned*)((const char*)(gbase) + (voff)[_i]), (PG8_LAS unsigned*)(lds + (bufoff) + ldsw + _i * 8192), 16, 0, 0); } while (0)
; #define PG8_LDA(dst, b, h) do { _Pragma("unroll") for (int m = 0; m < 4; ++m) _Pragma("unroll") for (int k = 0; k < 2; ++k) dst[m][k] = *(const PG8_LAS bf16x8*)(lds + PG8_SA(b, h) + aoff + m * 2048 + k * 1024); } while (0)
; #define PG8_LDB(dst, b, h) do { _Pragma("unroll") for (int n = 0; n < 2; ++n) _Pragma("unroll") for (int k = 0; k < 2; ++k) dst[n][k] = *(const PG8_LAS bf16x8*)(lds + PG8_SB(b, h) + boff + n * 2048 + k * 1024); } while (0)
; #define PG8_MMA(ai, bj, At, Bt) do { __builtin_amdgcn_s_setprio(1); _Pragma("unroll") for (int m = 0; m < 4; ++m) _Pragma("unroll") for (int n = 0; n < 2; ++n) _Pragma("unroll") for (int k = 0; k < 2; ++k) \
;         acc[ai][bj][m][n] = __builtin_amdgcn_mfma_f32_16x16x32_bf16(Bt[n][k], At[m][k], acc[ai][bj][m][n], 0, 0, 0); __builtin_amdgcn_s_setprio(0); } while (0)
; #define PG8_WAIT_V(n) asm volatile("s_waitcnt vmcnt(" #n ")" ::: "memory")
; #define PG8_WAIT_L(n) asm volatile("s_waitcnt lgkmcnt(" #n ")" ::: "memory")
; template <class Epi, class Sched, bool ALIGN_EPI = false, bool SP2 = false>
; __device__ __forceinline__ void gemm_phase(PG8_LAS unsigned char* lds, const Gemm g, const Sched& S, const Epi& E, const int tid_in) {
;     ...
;             const bool last = (t == nt - 2);
;             const char* a1 = cA + (size_t)(t + 1) * kstep;
;             const char* a2 = last ? nA : cA + (size_t)(t + 2) * kstep; const char* b2 = last ? nB : cB + (size_t)(t + 2) * kstep;
;             const char* a3 = a2 + kstep; const char* b3 = b2 + kstep;
;             if (last && has_next) S.a_ready(nxt);
;             if constexpr (SP2) {
;             PG8_LDB(B0, 0, 0); PG8_LDB(B1, 0, 1); PG8_SCHED; PG8_LDA(At, 0, 0); PG8_STAGE(PG8_SA(1, 1), a1 + hstep, voffA);
;             PG8_WAIT_V(8); PG8_WAIT_L(0); PG8_BAR; PG8_MMA(0, 0, At, B0); PG8_MMA(0, 1, At, B1); PG8_BAR; PG8_SCHED;
;             PG8_LDA(At, 0, 1); PG8_STAGE(PG8_SB(0, 0), b2, voffB); PG8_STAGE(PG8_SB(0, 1), b2 + hstep, voffB); PG8_STAGE(PG8_SA(0, 0), a2, voffA);
;             PG8_WAIT_V(8); PG8_WAIT_L(0); PG8_BAR; PG8_MMA(1, 0, At, B0); PG8_MMA(1, 1, At, B1); PG8_BAR; PG8_SCHED;
.LBB0_400:
	s_add_u32 s52, s40, 0xfffc0080
	s_addc_u32 s53, s41, -1
	s_add_i32 s87, 0, 0x10000
	s_cmp_eq_u32 s47, 12
	s_cselect_b32 s55, s9, s53
	s_cselect_b32 s54, s16, s52
	s_cselect_b32 s53, s17, s45
	s_cselect_b32 s52, s20, s21
	s_add_i32 s90, 0, 0x14000
	v_add_u32_e32 v60, s87, v180
	v_add_u32_e32 v158, s90, v180
	ds_read_b128 v[48:51], v60
	ds_read_b128 v[52:55], v60 offset:1024
	ds_read_b128 v[56:59], v60 offset:2048
	ds_read_b128 v[60:63], v60 offset:3072
	ds_read_b128 v[154:157], v158
	ds_read_b128 v[176:179], v158 offset:1024
	ds_read_b128 v[184:187], v158 offset:2048
	ds_read_b128 v[188:191], v158 offset:3072
	v_lshl_add_u64 v[158:159], s[40:41], 0, v[150:151]
	s_add_i32 m0, s58, 0xc000
	ds_read_b128 v[192:195], v182
	ds_read_b128 v[196:199], v182 offset:1024
	ds_read_b128 v[200:203], v182 offset:2048
	ds_read_b128 v[204:207], v182 offset:3072
	ds_read_b128 v[208:211], v182 offset:4096
	ds_read_b128 v[212:215], v182 offset:5120
	ds_read_b128 v[216:219], v182 offset:6144
	ds_read_b128 v[238:241], v182 offset:7168
	global_load_lds_dwordx4 v[158:159], off
	v_lshl_add_u64 v[158:159], s[40:41], 0, v[152:153]
	s_add_i32 m0, s58, 0xe000
	s_nop 0
	global_load_lds_dwordx4 v[158:159], off
	s_waitcnt vmcnt(8)
	s_waitcnt lgkmcnt(0)
	s_barrier
	s_waitcnt lgkmcnt(0)
	v_mfma_f32_16x16x32_bf16 v[140:143], v[48:51], v[192:195], v[140:143]
	v_mfma_f32_16x16x32_bf16 v[136:139], v[56:59], v[192:195], v[136:139]
	v_mfma_f32_16x16x32_bf16 v[124:127], v[48:51], v[200:203], v[124:127]
	v_mfma_f32_16x16x32_bf16 v[120:123], v[56:59], v[200:203], v[120:123]
	v_mfma_f32_16x16x32_bf16 v[108:111], v[48:51], v[208:211], v[108:111]
	v_mfma_f32_16x16x32_bf16 v[104:107], v[56:59], v[208:211], v[104:107]
	v_mfma_f32_16x16x32_bf16 v[92:95], v[48:51], v[216:219], v[92:95]
	v_mfma_f32_16x16x32_bf16 v[88:91], v[56:59], v[216:219], v[88:91]
	v_mfma_f32_16x16x32_bf16 v[140:143], v[52:55], v[196:199], v[140:143]
	v_mfma_f32_16x16x32_bf16 v[136:139], v[60:63], v[196:199], v[136:139]
	v_mfma_f32_16x16x32_bf16 v[124:127], v[52:55], v[204:207], v[124:127]
	v_mfma_f32_16x16x32_bf16 v[120:123], v[60:63], v[204:207], v[120:123]
	v_mfma_f32_16x16x32_bf16 v[108:111], v[52:55], v[212:215], v[108:111]
	v_mfma_f32_16x16x32_bf16 v[104:107], v[60:63], v[212:215], v[104:107]
	v_mfma_f32_16x16x32_bf16 v[92:95], v[52:55], v[238:241], v[92:95]
	v_mfma_f32_16x16x32_bf16 v[88:91], v[60:63], v[238:241], v[88:91]
	v_mfma_f32_16x16x32_bf16 v[132:135], v[154:157], v[192:195], v[132:135]
	v_mfma_f32_16x16x32_bf16 v[128:131], v[184:187], v[192:195], v[128:131]
	v_mfma_f32_16x16x32_bf16 v[116:119], v[154:157], v[200:203], v[116:119]
	v_mfma_f32_16x16x32_bf16 v[112:115], v[184:187], v[200:203], v[112:115]
	v_mfma_f32_16x16x32_bf16 v[100:103], v[154:157], v[208:211], v[100:103]
	v_mfma_f32_16x16x32_bf16 v[96:99], v[184:187], v[208:211], v[96:99]
	v_mfma_f32_16x16x32_bf16 v[84:87], v[154:157], v[216:219], v[84:87]
	v_mfma_f32_16x16x32_bf16 v[80:83], v[184:187], v[216:219], v[80:83]
	v_mfma_f32_16x16x32_bf16 v[132:135], v[176:179], v[196:199], v[132:135]
	v_mfma_f32_16x16x32_bf16 v[128:131], v[188:191], v[196:199], v[128:131]
	v_mfma_f32_16x16x32_bf16 v[116:119], v[176:179], v[204:207], v[116:119]
	v_mfma_f32_16x16x32_bf16 v[112:115], v[188:191], v[204:207], v[112:115]
	v_mfma_f32_16x16x32_bf16 v[100:103], v[176:179], v[212:215], v[100:103]
	v_mfma_f32_16x16x32_bf16 v[96:99], v[188:191], v[212:215], v[96:99]
	v_mfma_f32_16x16x32_bf16 v[84:87], v[176:179], v[238:241], v[84:87]
	v_mfma_f32_16x16x32_bf16 v[80:83], v[188:191], v[238:241], v[80:83]
	s_barrier
	s_add_i32 s87, s87, s57
	v_lshl_add_u64 v[158:159], s[52:53], 0, v[160:161]
	s_mov_b32 m0, s87
	ds_read_b128 v[192:195], v182 offset:16384
	ds_read_b128 v[196:199], v182 offset:17408
	ds_read_b128 v[200:203], v182 offset:18432
	ds_read_b128 v[204:207], v182 offset:19456
	ds_read_b128 v[208:211], v182 offset:20480
	ds_read_b128 v[212:215], v182 offset:21504
	ds_read_b128 v[216:219], v182 offset:22528
	ds_read_b128 v[238:241], v182 offset:23552
	global_load_lds_dwordx4 v[158:159], off
	s_add_i32 m0, s87, 0x2000
	s_add_u32 s88, s52, 0x40000
	v_lshl_add_u64 v[220:221], s[52:53], 0, v[144:145]
	s_addc_u32 s89, s53, 0
	s_add_i32 s87, s90, s57
	global_load_lds_dwordx4 v[220:221], off
	v_lshl_add_u64 v[242:243], s[88:89], 0, v[160:161]
	s_mov_b32 m0, s87
	v_lshl_add_u64 v[244:245], s[54:55], 0, v[146:147]
	global_load_lds_dwordx4 v[242:243], off
	v_lshl_add_u64 v[242:243], s[88:89], 0, v[144:145]
	s_add_i32 m0, s87, 0x2000
	s_nop 0
	global_load_lds_dwordx4 v[242:243], off
	v_lshl_add_u64 v[242:243], s[54:55], 0, v[148:149]
	s_mov_b32 m0, s58
	s_nop 0
	global_load_lds_dwordx4 v[242:243], off
	s_mov_b32 m0, s59
	s_nop 0
	global_load_lds_dwordx4 v[244:245], off
	s_waitcnt vmcnt(8)
	s_waitcnt lgkmcnt(0)
	s_barrier
; #define PG8_STAGE(bufoff, gbase, voff) do { _Pragma("unroll") for (int _i = 0; _i < 2; ++_i) \
;         __builtin_amdgcn_global_load_lds((const unsigned*)((const char*)(gbase) + (voff)[_i]), (PG8_LAS unsigned*)(lds + (bufoff) + ldsw + _i * 8192), 16, 0, 0); } while (0)
; #define PG8_LDA(dst, b, h) do { _Pragma("unroll") for (int m = 0; m < 4; ++m) _Pragma("unroll") for (int k = 0; k < 2; ++k) dst[m][k] = *(const PG8_LAS bf16x8*)(lds + PG8_SA(b, h) + aoff + m * 2048 + k * 1024); } while (0)
; #define PG8_LDB(dst, b, h) do { _Pragma("unroll") for (int n = 0; n < 2; ++n) _Pragma("unroll") for (int k = 0; k < 2; ++k) dst[n][k] = *(const PG8_LAS bf16x8*)(lds + PG8_SB(b, h) + boff + n * 2048 + k * 1024); } while (0)
; #define PG8_MMA(ai, bj, At, Bt) do { __builtin_amdgcn_s_setprio(1); _Pragma("unroll") for (int m = 0; m < 4; ++m) _Pragma("unroll") for (int n = 0; n < 2; ++n) _Pragma("unroll") for (int k = 0; k < 2; ++k) \
;         acc[ai][bj][m][n] = __builtin_amdgcn_mfma_f32_16x16x32_bf16(Bt[n][k], At[m][k], acc[ai][bj][m][n], 0, 0, 0); __builtin_amdgcn_s_setprio(0); } while (0)
; #define PG8_WAIT_V(n) asm volatile("s_waitcnt vmcnt(" #n ")" ::: "memory")
; #define PG8_WAIT_L(n) asm volatile("s_waitcnt lgkmcnt(" #n ")" ::: "memory")
; #define PG8_BAR __builtin_amdgcn_s_barrier()
; #define PG8_SCHED __builtin_amdgcn_sched_barrier(0)
; template <class Epi, class Sched, bool ALIGN_EPI = false, bool SP2 = false>
; __device__ __forceinline__ void gemm_phase(PG8_LAS unsigned char* lds, const Gemm g, const Sched& S, const Epi& E, const int tid_in) {
;     ...
;             PG8_WAIT_V(8); PG8_WAIT_L(0); PG8_BAR; PG8_MMA(0, 0, At, B0); PG8_MMA(0, 1, At, B1); PG8_BAR; PG8_SCHED;
;             PG8_LDA(At, 0, 1); PG8_STAGE(PG8_SB(0, 0), b2, voffB); PG8_STAGE(PG8_SB(0, 1), b2 + hstep, voffB); PG8_STAGE(PG8_SA(0, 0), a2, voffA);
;             PG8_WAIT_V(8); PG8_WAIT_L(0); PG8_BAR; PG8_MMA(1, 0, At, B0); PG8_MMA(1, 1, At, B1); PG8_BAR; PG8_SCHED;
;             PG8_LDB(B0, 1, 0); PG8_LDB(B1, 1, 1); PG8_SCHED; PG8_LDA(At, 1, 0); PG8_STAGE(PG8_SA(0, 1), a2 + hstep, voffA);
;             PG8_WAIT_V(8); PG8_WAIT_L(0); PG8_BAR; PG8_MMA(0, 0, At, B0); PG8_MMA(0, 1, At, B1); PG8_BAR; PG8_SCHED;
	s_waitcnt lgkmcnt(0)
	v_mfma_f32_16x16x32_bf16 v[76:79], v[48:51], v[192:195], v[76:79]
	v_mfma_f32_16x16x32_bf16 v[72:75], v[56:59], v[192:195], v[72:75]
	v_mfma_f32_16x16x32_bf16 v[44:47], v[48:51], v[200:203], v[44:47]
	v_mfma_f32_16x16x32_bf16 v[40:43], v[56:59], v[200:203], v[40:43]
	v_mfma_f32_16x16x32_bf16 v[28:31], v[48:51], v[208:211], v[28:31]
	v_mfma_f32_16x16x32_bf16 v[24:27], v[56:59], v[208:211], v[24:27]
	v_mfma_f32_16x16x32_bf16 v[12:15], v[48:51], v[216:219], v[12:15]
	v_mfma_f32_16x16x32_bf16 v[8:11], v[56:59], v[216:219], v[8:11]
	v_mfma_f32_16x16x32_bf16 v[76:79], v[52:55], v[196:199], v[76:79]
	v_mfma_f32_16x16x32_bf16 v[72:75], v[60:63], v[196:199], v[72:75]
	v_mfma_f32_16x16x32_bf16 v[44:47], v[52:55], v[204:207], v[44:47]
	v_mfma_f32_16x16x32_bf16 v[40:43], v[60:63], v[204:207], v[40:43]
	v_mfma_f32_16x16x32_bf16 v[28:31], v[52:55], v[212:215], v[28:31]
	v_mfma_f32_16x16x32_bf16 v[24:27], v[60:63], v[212:215], v[24:27]
	v_mfma_f32_16x16x32_bf16 v[12:15], v[52:55], v[238:241], v[12:15]
	v_mfma_f32_16x16x32_bf16 v[8:11], v[60:63], v[238:241], v[8:11]
	v_mfma_f32_16x16x32_bf16 v[36:39], v[154:157], v[200:203], v[36:39]
	v_mfma_f32_16x16x32_bf16 v[32:35], v[184:187], v[200:203], v[32:35]
	v_mfma_f32_16x16x32_bf16 v[20:23], v[154:157], v[208:211], v[20:23]
	v_mfma_f32_16x16x32_bf16 v[16:19], v[184:187], v[208:211], v[16:19]
	v_mfma_f32_16x16x32_bf16 v[4:7], v[154:157], v[216:219], v[4:7]
	v_mfma_f32_16x16x32_bf16 v[0:3], v[184:187], v[216:219], v[0:3]
	v_mfma_f32_16x16x32_bf16 v[48:51], v[154:157], v[192:195], v[68:71]
	v_mfma_f32_16x16x32_bf16 v[52:55], v[184:187], v[192:195], v[64:67]
	v_mfma_f32_16x16x32_bf16 v[36:39], v[176:179], v[204:207], v[36:39]
	v_mfma_f32_16x16x32_bf16 v[32:35], v[188:191], v[204:207], v[32:35]
	v_mfma_f32_16x16x32_bf16 v[20:23], v[176:179], v[212:215], v[20:23]
	v_mfma_f32_16x16x32_bf16 v[16:19], v[188:191], v[212:215], v[16:19]
	v_mfma_f32_16x16x32_bf16 v[4:7], v[176:179], v[238:241], v[4:7]
	v_mfma_f32_16x16x32_bf16 v[0:3], v[188:191], v[238:241], v[0:3]
	v_mfma_f32_16x16x32_bf16 v[48:51], v[176:179], v[196:199], v[48:51]
	v_mfma_f32_16x16x32_bf16 v[52:55], v[188:191], v[196:199], v[52:55]
	s_barrier
	s_add_i32 s87, 0, 0x18000
	s_add_i32 s88, 0, 0x1c000
	v_add_u32_e32 v68, s87, v180
	v_add_u32_e32 v188, s88, v180
	ds_read_b128 v[56:59], v68
	ds_read_b128 v[60:63], v68 offset:1024
	ds_read_b128 v[64:67], v68 offset:2048
	ds_read_b128 v[68:71], v68 offset:3072
	ds_read_b128 v[154:157], v188
	ds_read_b128 v[176:179], v188 offset:1024
	ds_read_b128 v[184:187], v188 offset:2048
	ds_read_b128 v[188:191], v188 offset:3072
	s_add_u32 s54, s54, 0x40000
	s_addc_u32 s55, s55, 0
	s_mov_b32 m0, s60
	v_lshl_add_u64 v[246:247], s[54:55], 0, v[148:149]
	ds_read_b128 v[192:195], v182 offset:32768
	ds_read_b128 v[196:199], v182 offset:33792
	ds_read_b128 v[200:203], v182 offset:34816
	ds_read_b128 v[204:207], v182 offset:35840
	ds_read_b128 v[208:211], v182 offset:36864
	ds_read_b128 v[212:215], v182 offset:37888
	ds_read_b128 v[216:219], v182 offset:38912
	ds_read_b128 v[238:241], v182 offset:39936
	global_load_lds_dwordx4 v[246:247], off
	v_lshl_add_u64 v[246:247], s[54:55], 0, v[146:147]
	s_mov_b32 m0, s61
	s_nop 0
	global_load_lds_dwordx4 v[246:247], off
	s_waitcnt vmcnt(8)
	s_waitcnt lgkmcnt(0)
	s_barrier
	s_waitcnt lgkmcnt(0)
	v_mfma_f32_16x16x32_bf16 v[140:143], v[56:59], v[192:195], v[140:143]
	v_mfma_f32_16x16x32_bf16 v[136:139], v[64:67], v[192:195], v[136:139]
	v_mfma_f32_16x16x32_bf16 v[124:127], v[56:59], v[200:203], v[124:127]
	v_mfma_f32_16x16x32_bf16 v[120:123], v[64:67], v[200:203], v[120:123]
	v_mfma_f32_16x16x32_bf16 v[108:111], v[56:59], v[208:211], v[108:111]
	v_mfma_f32_16x16x32_bf16 v[104:107], v[64:67], v[208:211], v[104:107]
	v_mfma_f32_16x16x32_bf16 v[92:95], v[56:59], v[216:219], v[92:95]
	v_mfma_f32_16x16x32_bf16 v[88:91], v[64:67], v[216:219], v[88:91]
	v_mfma_f32_16x16x32_bf16 v[140:143], v[60:63], v[196:199], v[140:143]
	v_mfma_f32_16x16x32_bf16 v[136:139], v[68:71], v[196:199], v[136:139]
	v_mfma_f32_16x16x32_bf16 v[124:127], v[60:63], v[204:207], v[124:127]
	v_mfma_f32_16x16x32_bf16 v[120:123], v[68:71], v[204:207], v[120:123]
	v_mfma_f32_16x16x32_bf16 v[108:111], v[60:63], v[212:215], v[108:111]
	v_mfma_f32_16x16x32_bf16 v[104:107], v[68:71], v[212:215], v[104:107]
	v_mfma_f32_16x16x32_bf16 v[92:95], v[60:63], v[238:241], v[92:95]
	v_mfma_f32_16x16x32_bf16 v[88:91], v[68:71], v[238:241], v[88:91]
	v_mfma_f32_16x16x32_bf16 v[132:135], v[154:157], v[192:195], v[132:135]
	v_mfma_f32_16x16x32_bf16 v[128:131], v[184:187], v[192:195], v[128:131]
	v_mfma_f32_16x16x32_bf16 v[116:119], v[154:157], v[200:203], v[116:119]
	v_mfma_f32_16x16x32_bf16 v[112:115], v[184:187], v[200:203], v[112:115]
	v_mfma_f32_16x16x32_bf16 v[100:103], v[154:157], v[208:211], v[100:103]
	v_mfma_f32_16x16x32_bf16 v[96:99], v[184:187], v[208:211], v[96:99]
	v_mfma_f32_16x16x32_bf16 v[84:87], v[154:157], v[216:219], v[84:87]
	v_mfma_f32_16x16x32_bf16 v[80:83], v[184:187], v[216:219], v[80:83]
	v_mfma_f32_16x16x32_bf16 v[132:135], v[176:179], v[196:199], v[132:135]
	v_mfma_f32_16x16x32_bf16 v[128:131], v[188:191], v[196:199], v[128:131]
	v_mfma_f32_16x16x32_bf16 v[116:119], v[176:179], v[204:207], v[116:119]
	v_mfma_f32_16x16x32_bf16 v[112:115], v[188:191], v[204:207], v[112:115]
	v_mfma_f32_16x16x32_bf16 v[100:103], v[176:179], v[212:215], v[100:103]
	v_mfma_f32_16x16x32_bf16 v[96:99], v[188:191], v[212:215], v[96:99]
	v_mfma_f32_16x16x32_bf16 v[84:87], v[176:179], v[238:241], v[84:87]
	v_mfma_f32_16x16x32_bf16 v[80:83], v[188:191], v[238:241], v[80:83]
	s_barrier
; #define PG8_STAGE(bufoff, gbase, voff) do { _Pragma("unroll") for (int _i = 0; _i < 2; ++_i) \
;         __builtin_amdgcn_global_load_lds((const unsigned*)((const char*)(gbase) + (voff)[_i]), (PG8_LAS unsigned*)(lds + (bufoff) + ldsw + _i * 8192), 16, 0, 0); } while (0)
; #define PG8_LDA(dst, b, h) do { _Pragma("unroll") for (int m = 0; m < 4; ++m) _Pragma("unroll") for (int k = 0; k < 2; ++k) dst[m][k] = *(const PG8_LAS bf16x8*)(lds + PG8_SA(b, h) + aoff + m * 2048 + k * 1024); } while (0)
; #define PG8_MMA(ai, bj, At, Bt) do { __builtin_amdgcn_s_setprio(1); _Pragma("unroll") for (int m = 0; m < 4; ++m) _Pragma("unroll") for (int n = 0; n < 2; ++n) _Pragma("unroll") for (int k = 0; k < 2; ++k) \
;         acc[ai][bj][m][n] = __builtin_amdgcn_mfma_f32_16x16x32_bf16(Bt[n][k], At[m][k], acc[ai][bj][m][n], 0, 0, 0); __builtin_amdgcn_s_setprio(0); } while (0)
; #define PG8_WAIT_V(n) asm volatile("s_waitcnt vmcnt(" #n ")" ::: "memory")
; #define PG8_WAIT_L(n) asm volatile("s_waitcnt lgkmcnt(" #n ")" ::: "memory")
; #define PG8_BAR __builtin_amdgcn_s_barrier()
; #define PG8_SCHED __builtin_amdgcn_sched_barrier(0)
; template <class Epi, class Sched, bool ALIGN_EPI = false, bool SP2 = false>
; __device__ __forceinline__ void gemm_phase(PG8_LAS unsigned char* lds, const Gemm g, const Sched& S, const Epi& E, const int tid_in) {
;     ...
;             PG8_WAIT_V(8); PG8_WAIT_L(0); PG8_BAR; PG8_MMA(0, 0, At, B0); PG8_MMA(0, 1, At, B1); PG8_BAR; PG8_SCHED;
;             PG8_LDA(At, 1, 1); PG8_STAGE(PG8_SB(1, 0), b3, voffB); PG8_STAGE(PG8_SB(1, 1), b3 + hstep, voffB); PG8_STAGE(PG8_SA(1, 0), a3, voffA);
;             PG8_WAIT_V(8); PG8_WAIT_L(0); PG8_BAR; PG8_MMA(1, 0, At, B0); PG8_MMA(1, 1, At, B1); PG8_BAR; PG8_SCHED;
	s_add_i32 s54, s87, s57
	v_lshl_add_u64 v[158:159], v[158:159], 0, s[26:27]
	s_mov_b32 m0, s54
	ds_read_b128 v[192:195], v182 offset:49152
	ds_read_b128 v[196:199], v182 offset:50176
	ds_read_b128 v[200:203], v182 offset:51200
	ds_read_b128 v[204:207], v182 offset:52224
	ds_read_b128 v[208:211], v182 offset:53248
	ds_read_b128 v[212:215], v182 offset:54272
	ds_read_b128 v[216:219], v182 offset:55296
	ds_read_b128 v[238:241], v182 offset:56320
	global_load_lds_dwordx4 v[158:159], off
	s_add_i32 m0, s54, 0x2000
	s_add_u32 s52, s52, 0x40080
	v_lshl_add_u64 v[158:159], v[220:221], 0, s[26:27]
	s_addc_u32 s53, s53, 0
	s_add_i32 s54, s88, s57
	global_load_lds_dwordx4 v[158:159], off
	v_lshl_add_u64 v[158:159], s[52:53], 0, v[160:161]
	s_mov_b32 m0, s54
	s_nop 0
	global_load_lds_dwordx4 v[158:159], off
	v_lshl_add_u64 v[158:159], s[52:53], 0, v[144:145]
	s_add_i32 m0, s54, 0x2000
	s_nop 0
	global_load_lds_dwordx4 v[158:159], off
	v_lshl_add_u64 v[158:159], v[242:243], 0, s[26:27]
	s_mov_b32 m0, s64
	s_nop 0
	global_load_lds_dwordx4 v[158:159], off
	v_lshl_add_u64 v[158:159], v[244:245], 0, s[26:27]
	s_mov_b32 m0, s65
	s_nop 0
	global_load_lds_dwordx4 v[158:159], off
	s_waitcnt vmcnt(8)
	s_waitcnt lgkmcnt(0)
	s_barrier
	s_waitcnt lgkmcnt(0)
	v_mfma_f32_16x16x32_bf16 v[76:79], v[56:59], v[192:195], v[76:79]
	v_mfma_f32_16x16x32_bf16 v[72:75], v[64:67], v[192:195], v[72:75]
	v_mfma_f32_16x16x32_bf16 v[44:47], v[56:59], v[200:203], v[44:47]
	v_mfma_f32_16x16x32_bf16 v[40:43], v[64:67], v[200:203], v[40:43]
	v_mfma_f32_16x16x32_bf16 v[28:31], v[56:59], v[208:211], v[28:31]
	v_mfma_f32_16x16x32_bf16 v[24:27], v[64:67], v[208:211], v[24:27]
	v_mfma_f32_16x16x32_bf16 v[12:15], v[56:59], v[216:219], v[12:15]
	v_mfma_f32_16x16x32_bf16 v[8:11], v[64:67], v[216:219], v[8:11]
	v_mfma_f32_16x16x32_bf16 v[76:79], v[60:63], v[196:199], v[76:79]
	v_mfma_f32_16x16x32_bf16 v[72:75], v[68:71], v[196:199], v[72:75]
	v_mfma_f32_16x16x32_bf16 v[44:47], v[60:63], v[204:207], v[44:47]
	v_mfma_f32_16x16x32_bf16 v[40:43], v[68:71], v[204:207], v[40:43]
	v_mfma_f32_16x16x32_bf16 v[28:31], v[60:63], v[212:215], v[28:31]
	v_mfma_f32_16x16x32_bf16 v[24:27], v[68:71], v[212:215], v[24:27]
	v_mfma_f32_16x16x32_bf16 v[12:15], v[60:63], v[238:241], v[12:15]
	v_mfma_f32_16x16x32_bf16 v[8:11], v[68:71], v[238:241], v[8:11]
	v_mfma_f32_16x16x32_bf16 v[48:51], v[154:157], v[192:195], v[48:51]
	v_mfma_f32_16x16x32_bf16 v[68:71], v[176:179], v[196:199], v[48:51]
	v_mfma_f32_16x16x32_bf16 v[48:51], v[184:187], v[192:195], v[52:55]
	v_mfma_f32_16x16x32_bf16 v[36:39], v[154:157], v[200:203], v[36:39]
	v_mfma_f32_16x16x32_bf16 v[32:35], v[184:187], v[200:203], v[32:35]
	v_mfma_f32_16x16x32_bf16 v[20:23], v[154:157], v[208:211], v[20:23]
	v_mfma_f32_16x16x32_bf16 v[16:19], v[184:187], v[208:211], v[16:19]
	v_mfma_f32_16x16x32_bf16 v[4:7], v[154:157], v[216:219], v[4:7]
	v_mfma_f32_16x16x32_bf16 v[0:3], v[184:187], v[216:219], v[0:3]
	v_mfma_f32_16x16x32_bf16 v[64:67], v[188:191], v[196:199], v[48:51]
	v_mfma_f32_16x16x32_bf16 v[36:39], v[176:179], v[204:207], v[36:39]
	v_mfma_f32_16x16x32_bf16 v[32:35], v[188:191], v[204:207], v[32:35]
	v_mfma_f32_16x16x32_bf16 v[20:23], v[176:179], v[212:215], v[20:23]
	v_mfma_f32_16x16x32_bf16 v[16:19], v[188:191], v[212:215], v[16:19]
	v_mfma_f32_16x16x32_bf16 v[4:7], v[176:179], v[238:241], v[4:7]
	v_mfma_f32_16x16x32_bf16 v[0:3], v[188:191], v[238:241], v[0:3]
	s_barrier
	s_add_i32 s47, s47, 2
	s_add_u32 s40, s40, 0x100
	s_addc_u32 s41, s41, 0
	s_add_u32 s21, s21, 0x100
	s_addc_u32 s45, s45, 0
	s_cmp_gt_u32 s47, 13
	s_cbranch_scc0 .LBB0_400
	s_and_b64 vcc, exec, s[36:37]
	s_cbranch_vccz .LBB0_403
	s_barrier
